# v76 plus retention state-update K2 transposed-fragment reads (dt 0-2) issued in two early batches into the freed Q registers; lgkmcnt re-derived by simulation
# baseline (speedup 1.0000x reference)
; #define LAS __attribute__((address_space(3)))
; #define LBAR() do { asm volatile("s_waitcnt lgkmcnt(0)" ::: "memory"); __builtin_amdgcn_s_barrier(); asm volatile("" ::: "memory"); } while (0)
; __device__ __forceinline__ void retention_unit(LAS unsigned char* lds, const Ptrs& P, int b, int h, int tid) {
;     ...
;         if (n < 32) {
; #pragma unroll
;             for (int j2 = 0; j2 < 2; ++j2) {
;                 const int jt = (w & 1) * 2 + j2; f32x4 a4 = (f32x4){0.f, 0.f, 0.f, 0.f};
; #pragma unroll
;                 for (int ks = 0; ks < 2; ++ks) {
;                     const bf16x8 qf = *(const LAS bf16x8*)(Qs + (16 * it3 + fr) * S72 + 32 * ks + 8 * fq), kf = *(const LAS bf16x8*)(Ks + (16 * jt + fr) * S72 + 32 * ks + 8 * fq);
;                     a4 = mfma16(kf, qf, a4); }
;                 a4 = a4 * decv[j2];
;                 v2u pw; pw.x = pk2(a4[0], a4[1]); pw.y = pk2(a4[2], a4[3]);
;                 *(LAS v2u*)(Ss + (16 * it3 + fr) * S72 + 16 * jt + 4 * fq) = pw;
;             }
;         }
;         LBAR();
;         if (n >= 1) {
; #pragma unroll
;             for (int it = 0; it < 4; ++it) { const int i = 16 * it + fr; const float mean = stat[i * 2], rstd = stat[i * 2 + 1]; const v2u sg = sgr[it];
;                 const f32x4 y = (op[it] - mean) * rstd * gng4 * (f32x4){bflo(sg.x), bfhi(sg.x), bflo(sg.y), bfhi(sg.y)};
;                 v2u pw; pw.x = pk2(y[0], y[1]); pw.y = pk2(y[2], y[3]);
;                 *(v2u*)(gol + ((size_t)(n - 1) * 64 + 16 * it) * 1024) = pw; }
;         }
;         if (n < 32) {
;             f32x4 o[4]; bf16x8 bst[2], bv[2];
; #pragma unroll
;             for (int ks = 0; ks < 2; ++ks) { bst[ks] = *(const LAS bf16x8*)(St + (16 * w + fr) * S72 + 32 * ks + 8 * fq); bv[ks] = tr_frag(bufc + ROFF_V, S144 * 2, w, ks, fq, fr); }
; #pragma unroll
;             for (int it = 0; it < 4; ++it) { o[it] = (f32x4){0.f, 0.f, 0.f, 0.f};
; #pragma unroll
;                 for (int ks = 0; ks < 2; ++ks) { const bf16x8 qf = *(const LAS bf16x8*)(Qs + (16 * it + fr) * S72 + 32 * ks + 8 * fq); o[it] = mfma16(bst[ks], qf, o[it]); }
;                 o[it] = o[it] * dqv[it];
; #pragma unroll
;                 for (int ks = 0; ks < 2; ++ks) { const bf16x8 sf = *(const LAS bf16x8*)(Ss + (16 * it + fr) * S72 + 32 * ks + 8 * fq); o[it] = mfma16(bv[ks], sf, o[it]); }
;             }
.LBB0_657:
	s_or_b64 exec, exec, s[18:19]
	v_lshl_add_u32 v60, v155, 1, s90
	v_add_u32_e32 v61, v60, v179
	s_waitcnt lgkmcnt(0)
	ds_read_b128 v[56:59], v61 offset:9216
	v_add_u32_e32 v75, v60, v62
	ds_read_b128 v[184:187], v61 offset:9280
	ds_read_b128 v[188:191], v75
	ds_read_b128 v[192:195], v75 offset:64
	v_add_u32_e32 v60, v60, v178
	s_waitcnt vmcnt(7)
	v_and_b32_e32 v61, 0xffff0000, v54
	v_add_u32_e32 v75, 0, v160
	v_add_u32_e32 v143, 0x21400, v75
	v_lshl_add_u64 v[120:121], s[26:27], 0, v[114:115]
	v_add3_u32 v204, s90, v82, v169
	s_waitcnt lgkmcnt(1)
	v_mfma_f32_16x16x32_bf16 v[56:59], v[56:59], v[188:191], 0
	s_add_i32 s18, s90, s87
	s_waitcnt vmcnt(5)
	v_lshlrev_b32_e32 v200, 16, v122
	v_and_b32_e32 v201, 0xffff0000, v122
	s_waitcnt lgkmcnt(0)
	v_mfma_f32_16x16x32_bf16 v[56:59], v[184:187], v[192:195], v[56:59]
	v_lshlrev_b32_e32 v122, 16, v123
	v_and_b32_e32 v123, 0xffff0000, v123
	v_add3_u32 v212, s90, v162, v170
	v_mov_b32_e32 v75, v74
	v_pk_mul_f32 v[18:19], v[74:75], v[18:19]
	s_nop 2
	v_pk_mul_f32 v[58:59], v[100:101], v[58:59]
	v_pk_mul_f32 v[56:57], v[98:99], v[56:57]
	v_pk_mul_f32 v[16:17], v[76:77], v[16:17]
	v_cvt_pk_bf16_f32 v56, v56, v57
	v_cvt_pk_bf16_f32 v57, v58, v59
	ds_write_b64 v177, v[56:57]
	ds_read_b128 v[56:59], v60 offset:9216
	ds_read_b128 v[184:187], v60 offset:9280
	ds_read_b128 v[216:219], v204
	ds_read_b128 v[220:223], v204 offset:64
	ds_read_b128 v[224:227], v204 offset:2304
	ds_read_b128 v[228:231], v204 offset:2368
	ds_read_b128 v[232:235], v204 offset:4608
	ds_read_b128 v[236:239], v204 offset:4672
	ds_read_b128 v[240:243], v204 offset:6912
	ds_read_b128 v[244:247], v204 offset:6976
	s_waitcnt lgkmcnt(9)
	v_mfma_f32_16x16x32_bf16 v[56:59], v[56:59], v[188:191], 0
	v_lshlrev_b32_e32 v60, 16, v54
	v_lshlrev_b32_e32 v188, 16, v55
	v_and_b32_e32 v189, 0xffff0000, v55
	s_waitcnt lgkmcnt(8)
	v_mfma_f32_16x16x32_bf16 v[54:57], v[184:187], v[192:195], v[56:59]
	v_mul_f32_e64 v14, v74, v14
	v_mul_f32_e64 v15, v75, v15
	v_pk_mul_f32 v[12:13], v[76:77], v[12:13]
	v_pk_mul_f32 v[10:11], v[74:75], v[10:11]
	v_add_co_u32_e32 v58, vcc, s66, v120
	v_pk_mul_f32 v[8:9], v[76:77], v[8:9]
	s_nop 1
	v_pk_mul_f32 v[56:57], v[94:95], v[56:57]
	v_pk_mul_f32 v[54:55], v[92:93], v[54:55]
	v_addc_co_u32_e32 v59, vcc, 0, v121, vcc
	v_cvt_pk_bf16_f32 v54, v54, v55
	v_cvt_pk_bf16_f32 v55, v56, v57
	ds_write_b64 v142, v[54:55]
	s_waitcnt lgkmcnt(0)
	s_barrier
	ds_read2_b64 v[54:57], v143 offset1:16
	ds_read_b128 v[184:187], v137
	v_pk_mul_f32 v[6:7], v[74:75], v[6:7]
	v_pk_mul_f32 v[4:5], v[76:77], v[4:5]
	v_lshl_add_u64 v[110:111], v[110:111], 0, s[8:9]
	s_waitcnt lgkmcnt(1)
	v_sub_f32_e32 v41, v41, v54
	v_sub_f32_e32 v40, v40, v54
	v_sub_f32_e32 v43, v43, v54
	v_sub_f32_e32 v42, v42, v54
	v_pk_mul_f32 v[42:43], v[54:55], v[42:43] op_sel:[1,0]
	v_pk_mul_f32 v[40:41], v[54:55], v[40:41] op_sel:[1,0]
	v_pk_mul_f32 v[42:43], v[2:3], v[42:43]
	v_pk_mul_f32 v[40:41], v[0:1], v[40:41]
	v_pk_mul_f32 v[42:43], v[42:43], v[188:189]
	v_pk_mul_f32 v[40:41], v[40:41], v[60:61]
	v_sub_f32_e32 v45, v45, v56
	v_cvt_pk_bf16_f32 v40, v40, v41
	v_cvt_pk_bf16_f32 v41, v42, v43
	v_sub_f32_e32 v44, v44, v56
	global_store_dwordx2 v[58:59], v[40:41], off
	v_sub_f32_e32 v41, v47, v56
	v_sub_f32_e32 v40, v46, v56
	v_pk_mul_f32 v[40:41], v[56:57], v[40:41] op_sel:[1,0]
	v_pk_mul_f32 v[42:43], v[56:57], v[44:45] op_sel:[1,0]
	ds_read2_b64 v[54:57], v143 offset0:32 offset1:48
	v_pk_mul_f32 v[42:43], v[0:1], v[42:43]
	v_pk_mul_f32 v[40:41], v[2:3], v[40:41]
	v_lshlrev_b32_e32 v44, 16, v52
	v_and_b32_e32 v45, 0xffff0000, v52
	v_lshlrev_b32_e32 v46, 16, v53
	v_and_b32_e32 v47, 0xffff0000, v53
	v_pk_mul_f32 v[40:41], v[40:41], v[46:47]
	v_pk_mul_f32 v[42:43], v[42:43], v[44:45]
	ds_read_b128 v[188:191], v137 offset:64
	v_cvt_pk_bf16_f32 v42, v42, v43
	v_cvt_pk_bf16_f32 v43, v40, v41
	v_add_co_u32_e32 v40, vcc, s67, v120
	s_nop 0
	v_addc_co_u32_e32 v41, vcc, 0, v121, vcc
	global_store_dwordx2 v[40:41], v[42:43], off
	s_waitcnt lgkmcnt(1)
	v_sub_f32_e32 v41, v49, v54
	v_sub_f32_e32 v40, v48, v54
	v_sub_f32_e32 v43, v51, v54
	v_sub_f32_e32 v42, v50, v54
	v_pk_mul_f32 v[40:41], v[54:55], v[40:41] op_sel:[1,0]
	v_pk_mul_f32 v[192:193], v[54:55], v[42:43] op_sel:[1,0]
	v_pk_mul_f32 v[196:197], v[0:1], v[40:41]
	s_waitcnt lgkmcnt(0)
	v_mfma_f32_16x16x32_bf16 v[40:43], v[184:187], v[216:219], 0
	v_add3_u32 v48, s18, v162, v168
	ds_read_b64_tr_b16 v[58:59], v48 offset:27648
	ds_read_b64_tr_b16 v[60:61], v48 offset:28800
	ds_read_b64_tr_b16 v[52:53], v48 offset:36864
	ds_read_b64_tr_b16 v[54:55], v48 offset:38016
	ds_read_b128 v[48:51], v129
	v_pk_mul_f32 v[192:193], v[2:3], v[192:193]
	v_mfma_f32_16x16x32_bf16 v[40:43], v[188:191], v[220:223], v[40:43]
	ds_read_b128 v[44:47], v129 offset:64
	v_pk_mul_f32 v[122:123], v[192:193], v[122:123]
	ds_read_b128 v[192:195], v129 offset:2304
	v_lshl_add_u64 v[112:113], v[112:113], 0, s[12:13]
	v_lshl_add_u64 v[114:115], v[114:115], 0, s[14:15]
	s_nop 2
	v_pk_mul_f32 v[42:43], v[108:109], v[42:43]
	v_pk_mul_f32 v[40:41], v[90:91], v[40:41]
	s_cmp_lg_u32 s89, 30
	v_lshl_add_u64 v[116:117], v[116:117], 0, s[12:13]
	s_waitcnt lgkmcnt(2)
	v_mfma_f32_16x16x32_bf16 v[40:43], v[58:61], v[48:51], v[40:43]
	s_waitcnt lgkmcnt(1)
	v_mfma_f32_16x16x32_bf16 v[40:43], v[52:55], v[44:47], v[40:43]
	s_waitcnt lgkmcnt(0)
	v_mfma_f32_16x16x32_bf16 v[48:51], v[184:187], v[224:227], 0
	s_waitcnt lgkmcnt(0)
; #define LAS __attribute__((address_space(3)))
; __device__ __forceinline__ unsigned pk2(float lo, float hi) { return pg8::cvt_pk_bf16(lo, hi); }
; __device__ __forceinline__ f32x4 mfma16(bf16x8 a, bf16x8 b, f32x4 c) { return __builtin_amdgcn_mfma_f32_16x16x32_bf16(a, b, c, 0, 0, 0); }
; __device__ __forceinline__ void retention_unit(LAS unsigned char* lds, const Ptrs& P, int b, int h, int tid) {
;     ...
;         if (n < 32) {
;             f32x4 o[4]; bf16x8 bst[2], bv[2];
; #pragma unroll
;             for (int ks = 0; ks < 2; ++ks) { bst[ks] = *(const LAS bf16x8*)(St + (16 * w + fr) * S72 + 32 * ks + 8 * fq); bv[ks] = tr_frag(bufc + ROFF_V, S144 * 2, w, ks, fq, fr); }
; #pragma unroll
;             for (int it = 0; it < 4; ++it) { o[it] = (f32x4){0.f, 0.f, 0.f, 0.f};
; #pragma unroll
;                 for (int ks = 0; ks < 2; ++ks) { const bf16x8 qf = *(const LAS bf16x8*)(Qs + (16 * it + fr) * S72 + 32 * ks + 8 * fq); o[it] = mfma16(bst[ks], qf, o[it]); }
;                 o[it] = o[it] * dqv[it];
; #pragma unroll
;                 for (int ks = 0; ks < 2; ++ks) { const bf16x8 sf = *(const LAS bf16x8*)(Ss + (16 * it + fr) * S72 + 32 * ks + 8 * fq); o[it] = mfma16(bv[ks], sf, o[it]); }
;             }
; #pragma unroll
;             for (int dt = 0; dt < 4; ++dt) { st[dt] = st[dt] * dch;
; #pragma unroll
;                 for (int ks = 0; ks < 2; ++ks) { const bf16x8 kf = tr_frag(bufc + ROFF_K2, S72 * 2, dt, ks, fq, fr); st[dt] = mfma16(kf, bv[ks], st[dt]); }
;                 v2u pw; pw.x = pk2(st[dt][0], st[dt][1]); pw.y = pk2(st[dt][2], st[dt][3]);
;                 *(LAS v2u*)(St + (16 * w + fr) * S72 + 16 * dt + 4 * fq) = pw; }
; #pragma unroll
;             for (int it = 0; it < 4; ++it) { const f32x4 v = o[it]; typedef float f32x2 __attribute__((ext_vector_type(2)));
;                 *(LAS f32x2*)(part + ((16 * it + fr) * 32 + w * 4 + fq) * 2) = (f32x2){(v[0] + v[1]) + (v[2] + v[3]), (v[0] * v[0] + v[1] * v[1]) + (v[2] * v[2] + v[3] * v[3])};
;                 op[it] = v; }
	v_mfma_f32_16x16x32_bf16 v[44:47], v[188:191], v[228:231], v[48:51]
	ds_read_b64_tr_b16 v[216:217], v212 offset:18432
	ds_read_b64_tr_b16 v[218:219], v212 offset:19008
	ds_read_b64_tr_b16 v[220:221], v212 offset:23040
	ds_read_b64_tr_b16 v[222:223], v212 offset:23616
	ds_read_b64_tr_b16 v[224:225], v212 offset:18464
	ds_read_b64_tr_b16 v[226:227], v212 offset:19040
	ds_read_b64_tr_b16 v[228:229], v212 offset:23072
	ds_read_b64_tr_b16 v[230:231], v212 offset:23648
	s_nop 5
	ds_read_b128 v[48:51], v129 offset:2368
	s_nop 0
	v_pk_mul_f32 v[46:47], v[106:107], v[46:47]
	v_pk_mul_f32 v[44:45], v[78:79], v[44:45]
	s_nop 1
	v_mfma_f32_16x16x32_bf16 v[44:47], v[58:61], v[192:195], v[44:47]
	v_mul_f32_e64 v192, v196, v200
	v_mul_f32_e64 v193, v197, v201
	ds_read_b128 v[200:203], v129 offset:4608
	v_cvt_pk_bf16_f32 v192, v192, v193
	s_waitcnt lgkmcnt(1)
	v_mfma_f32_16x16x32_bf16 v[44:47], v[52:55], v[48:51], v[44:47]
	v_cvt_pk_bf16_f32 v193, v122, v123
	v_add_co_u32_e32 v122, vcc, s68, v120
	v_sub_f32_e32 v197, v23, v56
	s_nop 0
	v_addc_co_u32_e32 v123, vcc, 0, v121, vcc
	global_store_dwordx2 v[122:123], v[192:193], off
	s_waitcnt lgkmcnt(0)
	v_mfma_f32_16x16x32_bf16 v[48:51], v[184:187], v[232:235], 0
	v_sub_f32_e32 v123, v21, v56
	v_sub_f32_e32 v122, v20, v56
	v_sub_f32_e32 v196, v22, v56
	s_waitcnt lgkmcnt(0)
	v_mfma_f32_16x16x32_bf16 v[48:51], v[188:191], v[236:239], v[48:51]
	ds_read_b64_tr_b16 v[232:233], v212 offset:18496
	ds_read_b64_tr_b16 v[234:235], v212 offset:19072
	ds_read_b64_tr_b16 v[236:237], v212 offset:23104
	ds_read_b64_tr_b16 v[238:239], v212 offset:23680
	ds_read_b128 v[192:195], v129 offset:4672
	v_pk_mul_f32 v[196:197], v[56:57], v[196:197] op_sel:[1,0]
	v_pk_mul_f32 v[56:57], v[56:57], v[122:123] op_sel:[1,0]
	v_pk_mul_f32 v[122:123], v[2:3], v[196:197]
	v_pk_mul_f32 v[56:57], v[0:1], v[56:57]
	s_nop 2
	v_pk_mul_f32 v[50:51], v[104:105], v[50:51]
	v_pk_mul_f32 v[48:49], v[86:87], v[48:49]
	s_waitcnt vmcnt(7)
	v_lshlrev_b32_e32 v196, 16, v118
	v_and_b32_e32 v197, 0xffff0000, v118
	v_mfma_f32_16x16x32_bf16 v[48:51], v[58:61], v[200:203], v[48:51]
	s_waitcnt lgkmcnt(0)
	v_mfma_f32_16x16x32_bf16 v[16:19], v[216:219], v[58:61], v[16:19]
	s_waitcnt lgkmcnt(0)
	v_mfma_f32_16x16x32_bf16 v[16:19], v[220:223], v[52:55], v[16:19]
	v_mfma_f32_16x16x32_bf16 v[48:51], v[52:55], v[192:195], v[48:51]
	ds_read_b128 v[204:207], v129 offset:6912
	ds_read_b128 v[208:211], v129 offset:6976
	s_nop 2
	v_cvt_pk_bf16_f32 v20, v16, v17
	v_cvt_pk_bf16_f32 v21, v18, v19
	ds_write_b64 v132, v[20:21]
	s_waitcnt lgkmcnt(3)
	v_mfma_f32_16x16x32_bf16 v[184:187], v[184:187], v[240:243], 0
	s_waitcnt lgkmcnt(0)
	v_mfma_f32_16x16x32_bf16 v[12:15], v[224:227], v[58:61], v[12:15]
	s_waitcnt lgkmcnt(0)
	v_mfma_f32_16x16x32_bf16 v[12:15], v[228:231], v[52:55], v[12:15]
	v_mfma_f32_16x16x32_bf16 v[184:187], v[188:191], v[244:247], v[184:187]
	s_nop 6
	v_cvt_pk_bf16_f32 v20, v12, v13
	v_cvt_pk_bf16_f32 v21, v14, v15
	ds_write_b64 v132, v[20:21] offset:32
	s_waitcnt lgkmcnt(0)
	v_mfma_f32_16x16x32_bf16 v[8:11], v[232:235], v[58:61], v[8:11]
	v_mul_f32_e64 v186, v96, v186
	v_mul_f32_e64 v187, v97, v187
	v_pk_mul_f32 v[184:185], v[88:89], v[184:185]
	v_lshlrev_b32_e32 v20, 16, v119
	s_waitcnt lgkmcnt(0)
	v_mfma_f32_16x16x32_bf16 v[8:11], v[236:239], v[52:55], v[8:11]
	v_and_b32_e32 v21, 0xffff0000, v119
	v_pk_mul_f32 v[20:21], v[122:123], v[20:21]
	v_mfma_f32_16x16x32_bf16 v[184:187], v[58:61], v[204:207], v[184:187]
	s_nop 4
	v_cvt_pk_bf16_f32 v22, v8, v9
	v_cvt_pk_bf16_f32 v23, v10, v11
	ds_write_b64 v132, v[22:23] offset:64
	ds_read_b64_tr_b16 v[188:189], v212 offset:18528
	ds_read_b64_tr_b16 v[190:191], v212 offset:19104
	v_pk_mul_f32 v[22:23], v[56:57], v[196:197]
	v_cvt_pk_bf16_f32 v57, v20, v21
	v_cvt_pk_bf16_f32 v56, v22, v23
	v_mfma_f32_16x16x32_bf16 v[20:23], v[52:55], v[208:211], v[184:187]
	s_nop 2
	ds_read_b64_tr_b16 v[184:185], v212 offset:23136
	ds_read_b64_tr_b16 v[186:187], v212 offset:23712
	s_waitcnt lgkmcnt(2)
	v_mfma_f32_16x16x32_bf16 v[4:7], v[188:191], v[58:61], v[4:7]
	v_add_co_u32_e32 v58, vcc, s69, v120
	s_waitcnt lgkmcnt(0)
	v_mfma_f32_16x16x32_bf16 v[4:7], v[184:187], v[52:55], v[4:7]
	v_addc_co_u32_e32 v59, vcc, 0, v121, vcc
	global_store_dwordx2 v[58:59], v[56:57], off
	v_mul_f32_e32 v55, v41, v41
	v_mul_f32_e32 v57, v42, v42
	s_nop 3
	v_cvt_pk_bf16_f32 v52, v4, v5
	v_cvt_pk_bf16_f32 v53, v6, v7
	ds_write_b64 v132, v[52:53] offset:96
	v_mul_f32_e32 v53, v40, v40
	v_mul_f32_e32 v59, v43, v43
	v_mov_b32_e32 v52, v40
	v_mov_b32_e32 v54, v41
	v_mov_b32_e32 v56, v42
	v_mov_b32_e32 v58, v43
	v_pk_add_f32 v[52:53], v[52:53], v[54:55]
	v_pk_add_f32 v[54:55], v[56:57], v[58:59]
	v_mul_f32_e32 v57, v46, v46
	v_pk_add_f32 v[52:53], v[52:53], v[54:55]
	ds_write_b64 v133, v[52:53]
	v_mul_f32_e32 v53, v44, v44
	v_mul_f32_e32 v55, v45, v45
	v_mul_f32_e32 v59, v47, v47
	v_mov_b32_e32 v52, v44
	v_mov_b32_e32 v54, v45
	v_mov_b32_e32 v56, v46
	v_mov_b32_e32 v58, v47
	v_pk_add_f32 v[52:53], v[52:53], v[54:55]
	v_pk_add_f32 v[54:55], v[56:57], v[58:59]
	v_mul_f32_e32 v57, v50, v50
	v_pk_add_f32 v[52:53], v[52:53], v[54:55]
	ds_write_b64 v134, v[52:53]
	v_mul_f32_e32 v53, v48, v48
	v_mul_f32_e32 v55, v49, v49
	v_mul_f32_e32 v59, v51, v51
	v_mov_b32_e32 v52, v48
	v_mov_b32_e32 v54, v49
	v_mov_b32_e32 v56, v50
	v_mov_b32_e32 v58, v51
	v_pk_add_f32 v[52:53], v[52:53], v[54:55]
	v_pk_add_f32 v[54:55], v[56:57], v[58:59]
	v_mul_f32_e32 v57, v22, v22
	v_pk_add_f32 v[52:53], v[52:53], v[54:55]
	ds_write_b64 v135, v[52:53]
	v_mul_f32_e32 v53, v20, v20
	v_mul_f32_e32 v55, v21, v21
	v_mul_f32_e32 v59, v23, v23
	v_mov_b32_e32 v52, v20
	v_mov_b32_e32 v54, v21
	v_mov_b32_e32 v56, v22
	v_mov_b32_e32 v58, v23
	v_pk_add_f32 v[52:53], v[52:53], v[54:55]
	v_pk_add_f32 v[54:55], v[56:57], v[58:59]
	s_nop 0
	v_pk_add_f32 v[52:53], v[52:53], v[54:55]
	ds_write_b64 v136, v[52:53]
	s_cbranch_scc0 .LBB0_660
